# grid barrier: non-leader workgroups wait on the cross-XCC release generation directly instead of their XCC's generation (one release hop less per barrier)
# speedup vs baseline: 1.0065x; 1.0065x over previous
; DI unsigned xb_ld(unsigned* p) { return __hip_atomic_load(p, __ATOMIC_RELAXED, __HIP_MEMORY_SCOPE_AGENT); }
; DI unsigned xb_add(unsigned* p, unsigned v) { return __hip_atomic_fetch_add(p, v, __ATOMIC_RELAXED, __HIP_MEMORY_SCOPE_AGENT); }
; DI void xcd_barrier_complete(unsigned* bar, unsigned x, unsigned& nloc, unsigned& nx) {
;   const unsigned G = gridDim.x;
;   unsigned sum, cnt, mine, sp = 0u;
;   for (;;) {
;     sum = 0u; cnt = 0u; mine = 0u;
; #pragma unroll
;     for (unsigned j = 0; j < 16; ++j) { const unsigned c = xb_ld(&bar[XB_XCNT(j)]); sum += c; cnt += (c > 0u) ? 1u : 0u; mine = (j == x) ? c : mine; }
;     if (sum == G) break;
;     __builtin_amdgcn_s_sleep(1);
;     if ((++sp & 255u) == 0u) { if (xb_ld(&bar[XB_TMO])) break; if (sp > XB_SPIN_CAP) { atomicAdd(&bar[XB_TMO], 1u); break; } }
;   }
;   nloc = mine > 0u ? mine : 1u; nx = cnt > 0u ? cnt : 1u;
; }
; template <bool FIRST>
; DI void xcd_barrier(XcdBarrier& b) {
;   asm volatile("s_waitcnt vmcnt(0)" ::: "memory");
;   __syncthreads();
;   if (threadIdx.x == 0) {
;     unsigned* bar = b.bar;
;     asm volatile("" : "+s"(bar));
;     __builtin_amdgcn_s_waitcnt(0);
;     const unsigned bx = b.st[2];
;     if (FIRST) { unsigned n0, n1; xcd_barrier_complete(bar, bx, n0, n1); b.st[0] = n0; b.st[1] = n1; }
;     const unsigned nloc = b.st[0], nx = b.st[1];
;     const unsigned old = xb_add(&bar[XB_XSUB(bx)], 1u);
;     const unsigned gen = old / nloc;
;     if (old + 1u == (gen + 1u) * nloc) {
;       __builtin_amdgcn_fence(__ATOMIC_RELEASE, "agent");
;       asm volatile("s_waitcnt vmcnt(0)" ::: "memory");
;       const unsigned og = xb_add(&bar[XB_TOP], 1u);
;       const unsigned tg = og / nx;
;       if (og + 1u == (tg + 1u) * nx) xb_add(&bar[XB_TOPGEN], 1u);
;       else XB_SPIN(xb_ld(&bar[XB_TOPGEN]) == tg, bar);
;       __builtin_amdgcn_fence(__ATOMIC_ACQUIRE, "agent");
;       xb_add(&bar[XB_XGEN(bx)], 1u);
;       asm volatile("s_waitcnt vmcnt(0)" ::: "memory");
;     } else {
;       XB_SPIN(xb_ld(&bar[XB_XGEN(bx)]) == gen, bar);
;       __builtin_amdgcn_fence(__ATOMIC_ACQUIRE, "agent");
;       asm volatile("s_waitcnt vmcnt(0)" ::: "memory");
;     }
.LBB0_76:
	s_or_b64 exec, exec, s[0:1]
	s_cmp_eq_u32 s33, 15
	s_cselect_b64 vcc, -1, 0
	s_cmp_eq_u32 s33, 14
	s_cselect_b64 s[0:1], -1, 0
	s_cmp_eq_u32 s33, 13
	s_cselect_b64 s[4:5], -1, 0
	s_cmp_eq_u32 s33, 12
	s_cselect_b64 s[6:7], -1, 0
	s_cmp_eq_u32 s33, 11
	s_cselect_b64 s[8:9], -1, 0
	s_cmp_eq_u32 s33, 10
	s_cselect_b64 s[10:11], -1, 0
	s_cmp_eq_u32 s33, 9
	s_cselect_b64 s[12:13], -1, 0
	s_cmp_eq_u32 s33, 8
	s_cselect_b64 s[14:15], -1, 0
	s_cmp_eq_u32 s33, 7
	s_cselect_b64 s[16:17], -1, 0
	s_cmp_eq_u32 s33, 6
	s_cselect_b64 s[18:19], -1, 0
	s_cmp_eq_u32 s33, 5
	s_cselect_b64 s[20:21], -1, 0
	s_cmp_eq_u32 s33, 4
	s_cselect_b64 s[22:23], -1, 0
	s_cmp_eq_u32 s33, 3
	s_cselect_b64 s[24:25], -1, 0
	s_cmp_eq_u32 s33, 2
	s_cselect_b64 s[26:27], -1, 0
	s_cmp_eq_u32 s33, 1
	s_cselect_b64 s[28:29], -1, 0
	s_cmp_eq_u32 s33, 0
	s_cselect_b64 s[30:31], -1, 0
	v_cndmask_b32_e64 v0, 0, v25, s[30:31]
	v_cndmask_b32_e64 v0, v0, v10, s[28:29]
	v_cndmask_b32_e64 v0, v0, v11, s[26:27]
	v_cndmask_b32_e64 v0, v0, v12, s[24:25]
	v_cndmask_b32_e64 v0, v0, v13, s[22:23]
	v_cndmask_b32_e64 v0, v0, v14, s[20:21]
	v_cndmask_b32_e64 v0, v0, v15, s[18:19]
	v_cndmask_b32_e64 v0, v0, v16, s[16:17]
	v_cndmask_b32_e64 v0, v0, v17, s[14:15]
	v_cndmask_b32_e64 v0, v0, v18, s[12:13]
	v_cndmask_b32_e64 v0, v0, v19, s[10:11]
	v_cndmask_b32_e64 v0, v0, v20, s[8:9]
	v_cndmask_b32_e64 v0, v0, v21, s[6:7]
	v_cndmask_b32_e64 v0, v0, v22, s[4:5]
	v_cndmask_b32_e64 v0, v0, v23, s[0:1]
	v_cndmask_b32_e32 v0, v0, v24, vcc
	v_cmp_ne_u32_e32 vcc, 0, v25
	s_lshl_b32 s22, s33, 6
	s_mov_b32 s39, 0
	v_cndmask_b32_e64 v1, 0, 1, vcc
	v_cmp_ne_u32_e32 vcc, 0, v10
	s_add_i32 s38, s22, 0x500
	v_max_u32_e32 v0, 1, v0
	v_addc_co_u32_e32 v1, vcc, 0, v1, vcc
	v_cmp_ne_u32_e32 vcc, 0, v11
	s_lshl_b64 s[0:1], s[38:39], 2
	s_add_u32 s0, s34, s0
	v_cndmask_b32_e64 v2, 0, 1, vcc
	v_cmp_ne_u32_e32 vcc, 0, v12
	s_addc_u32 s1, s35, s1
	s_nop 0
	v_addc_co_u32_e32 v1, vcc, v1, v2, vcc
	v_cmp_ne_u32_e32 vcc, 0, v13
	s_nop 1
	v_cndmask_b32_e64 v2, 0, 1, vcc
	v_cmp_ne_u32_e32 vcc, 0, v14
	s_nop 1
	v_addc_co_u32_e32 v1, vcc, v1, v2, vcc
	v_cmp_ne_u32_e32 vcc, 0, v15
	s_nop 1
	v_cndmask_b32_e64 v2, 0, 1, vcc
	v_cmp_ne_u32_e32 vcc, 0, v16
	s_nop 1
	v_addc_co_u32_e32 v1, vcc, v1, v2, vcc
	v_cmp_ne_u32_e32 vcc, 0, v17
	s_nop 1
	v_cndmask_b32_e64 v2, 0, 1, vcc
	v_cmp_ne_u32_e32 vcc, 0, v18
	s_nop 1
	v_addc_co_u32_e32 v1, vcc, v1, v2, vcc
	v_cmp_ne_u32_e32 vcc, 0, v19
	s_nop 1
	v_cndmask_b32_e64 v2, 0, 1, vcc
	v_cmp_ne_u32_e32 vcc, 0, v20
	s_nop 1
	v_addc_co_u32_e32 v1, vcc, v1, v2, vcc
	v_cmp_ne_u32_e32 vcc, 0, v21
	s_nop 1
	v_cndmask_b32_e64 v2, 0, 1, vcc
	v_cmp_ne_u32_e32 vcc, 0, v22
	s_nop 1
	v_addc_co_u32_e32 v1, vcc, v1, v2, vcc
	v_cmp_ne_u32_e32 vcc, 0, v23
	s_nop 1
	v_cndmask_b32_e64 v2, 0, 1, vcc
	v_cmp_ne_u32_e32 vcc, 0, v24
	s_nop 1
	v_addc_co_u32_e32 v1, vcc, v1, v2, vcc
	v_mov_b32_e32 v2, 0x12000
	v_max_u32_e32 v1, 1, v1
	ds_write_b32 v2, v0
	v_mov_b32_e32 v0, 0x12004
	ds_write_b32 v0, v1
	ds_read_b32 v4, v2
	ds_read_b32 v1, v0
	v_mov_b64_e32 v[2:3], s[0:1]
	v_mov_b32_e32 v0, 1
	flat_atomic_add v2, v[2:3], v0 sc0
	s_waitcnt lgkmcnt(0)
	v_cvt_f32_u32_e32 v0, v4
	v_sub_u32_e32 v3, 0, v4
	v_rcp_iflag_f32_e32 v0, v0
	s_nop 0
	v_mul_f32_e32 v0, 0x4f7ffffe, v0
	v_cvt_u32_f32_e32 v0, v0
	v_mul_lo_u32 v3, v3, v0
	v_mul_hi_u32 v3, v0, v3
	v_add_u32_e32 v0, v0, v3
	s_waitcnt vmcnt(0)
	v_mul_hi_u32 v0, v2, v0
	v_mul_lo_u32 v3, v0, v4
	v_sub_u32_e32 v3, v2, v3
	v_add_u32_e32 v5, 1, v0
	v_cmp_ge_u32_e32 vcc, v3, v4
	v_add_u32_e32 v2, 1, v2
	s_nop 0
	v_cndmask_b32_e32 v0, v0, v5, vcc
	v_sub_u32_e32 v5, v3, v4
	v_cndmask_b32_e32 v3, v3, v5, vcc
	v_add_u32_e32 v5, 1, v0
	v_cmp_ge_u32_e32 vcc, v3, v4
	s_nop 1
	v_cndmask_b32_e32 v0, v0, v5, vcc
	v_mul_lo_u32 v3, v4, v0
	v_add_u32_e32 v3, v3, v4
	v_cmp_ne_u32_e32 vcc, v2, v3
	s_and_saveexec_b64 s[0:1], vcc
	s_xor_b64 s[0:1], exec, s[0:1]
	s_cbranch_execz .LBB0_89
	s_add_i32 s38, s22, 0x900
	s_add_u32 s6, s34, 0x3500
	s_addc_u32 s7, s35, 0
	v_mov_b64_e32 v[2:3], s[6:7]
	global_load_dword v1, v[2:3], off sc1
	s_waitcnt vmcnt(0) lgkmcnt(0)
	v_cmp_eq_u32_e32 vcc, v1, v0
	s_and_saveexec_b64 s[4:5], vcc
	s_cbranch_execz .LBB0_88
	s_mov_b32 s23, 1
	s_mov_b64 s[8:9], 0
	s_branch .LBB0_80

; DI unsigned xb_ld(unsigned* p) { return __hip_atomic_load(p, __ATOMIC_RELAXED, __HIP_MEMORY_SCOPE_AGENT); }
; DI unsigned xb_add(unsigned* p, unsigned v) { return __hip_atomic_fetch_add(p, v, __ATOMIC_RELAXED, __HIP_MEMORY_SCOPE_AGENT); }
; #define XB_SPIN(cond, bar) do { unsigned _sp = 0; while (cond) { __builtin_amdgcn_s_sleep(1); \
;     if ((++_sp & 255u) == 0u) { if (xb_ld(&(bar)[XB_TMO])) break; if (_sp > XB_SPIN_CAP) { atomicAdd(&(bar)[XB_TMO], 1u); break; } } } } while (0)
; template <bool FIRST>
; DI void xcd_barrier(XcdBarrier& b) {
;   asm volatile("s_waitcnt vmcnt(0)" ::: "memory");
;   __syncthreads();
;   if (threadIdx.x == 0) {
;     unsigned* bar = b.bar;
;     asm volatile("" : "+s"(bar));
;     __builtin_amdgcn_s_waitcnt(0);
;     const unsigned bx = b.st[2];
;     if (FIRST) { unsigned n0, n1; xcd_barrier_complete(bar, bx, n0, n1); b.st[0] = n0; b.st[1] = n1; }
;     const unsigned nloc = b.st[0], nx = b.st[1];
;     const unsigned old = xb_add(&bar[XB_XSUB(bx)], 1u);
;     const unsigned gen = old / nloc;
;     if (old + 1u == (gen + 1u) * nloc) {
;       __builtin_amdgcn_fence(__ATOMIC_RELEASE, "agent");
;       asm volatile("s_waitcnt vmcnt(0)" ::: "memory");
;       const unsigned og = xb_add(&bar[XB_TOP], 1u);
;       const unsigned tg = og / nx;
;       if (og + 1u == (tg + 1u) * nx) xb_add(&bar[XB_TOPGEN], 1u);
;       else XB_SPIN(xb_ld(&bar[XB_TOPGEN]) == tg, bar);
;       __builtin_amdgcn_fence(__ATOMIC_ACQUIRE, "agent");
;       xb_add(&bar[XB_XGEN(bx)], 1u);
;       asm volatile("s_waitcnt vmcnt(0)" ::: "memory");
;     } else {
;       XB_SPIN(xb_ld(&bar[XB_XGEN(bx)]) == gen, bar);
.LBB0_124:
	s_mul_i32 s0, s48, 6
	s_add_i32 s28, s0, 2
	s_cmp_ge_i32 s28, s59
	s_cbranch_scc1 .LBB0_156
	s_waitcnt vmcnt(0)
	s_waitcnt lgkmcnt(0)
	s_barrier
	s_and_saveexec_b64 s[0:1], s[60:61]
	s_cbranch_execz .LBB0_155
	v_readlane_b32 s4, v253, 1
	v_readlane_b32 s5, v253, 2
	s_waitcnt vmcnt(0) expcnt(0) lgkmcnt(0)
	ds_read_b32 v0, v163
	ds_read_b32 v4, v172
	ds_read_b32 v1, v173
	s_waitcnt lgkmcnt(2)
	v_readfirstlane_b32 s2, v0
	s_lshl_b32 s29, s2, 6
	s_add_i32 s2, s29, 0x500
	s_lshl_b64 s[6:7], s[2:3], 2
	s_add_u32 s6, s4, s6
	s_addc_u32 s7, s5, s7
	v_mov_b64_e32 v[2:3], s[6:7]
	flat_atomic_add v2, v[2:3], v174 sc0
	s_waitcnt lgkmcnt(0)
	v_cvt_f32_u32_e32 v0, v4
	v_sub_u32_e32 v3, 0, v4
	v_rcp_iflag_f32_e32 v0, v0
	s_nop 0
	v_mul_f32_e32 v0, 0x4f7ffffe, v0
	v_cvt_u32_f32_e32 v0, v0
	v_mul_lo_u32 v3, v3, v0
	v_mul_hi_u32 v3, v0, v3
	v_add_u32_e32 v0, v0, v3
	s_waitcnt vmcnt(0)
	v_mul_hi_u32 v0, v2, v0
	v_mul_lo_u32 v3, v0, v4
	v_sub_u32_e32 v3, v2, v3
	v_add_u32_e32 v5, 1, v0
	v_cmp_ge_u32_e32 vcc, v3, v4
	v_add_u32_e32 v2, 1, v2
	s_nop 0
	v_cndmask_b32_e32 v0, v0, v5, vcc
	v_sub_u32_e32 v5, v3, v4
	v_cndmask_b32_e32 v3, v3, v5, vcc
	v_add_u32_e32 v5, 1, v0
	v_cmp_ge_u32_e32 vcc, v3, v4
	s_nop 1
	v_cndmask_b32_e32 v0, v0, v5, vcc
	v_mul_lo_u32 v3, v4, v0
	v_add_u32_e32 v3, v3, v4
	v_cmp_ne_u32_e32 vcc, v2, v3
	s_and_saveexec_b64 s[6:7], vcc
	s_xor_b64 s[6:7], exec, s[6:7]
	s_cbranch_execz .LBB0_139
	s_add_i32 s2, s29, 0x900
	s_add_u32 s10, s4, 0x3500
	s_addc_u32 s11, s5, 0
	v_mov_b64_e32 v[2:3], s[10:11]
	global_load_dword v1, v[2:3], off sc1
	s_waitcnt vmcnt(0) lgkmcnt(0)
	v_cmp_eq_u32_e32 vcc, v1, v0
	s_and_saveexec_b64 s[8:9], vcc
	s_cbranch_execz .LBB0_138
	s_mov_b32 s2, 1
	s_mov_b64 s[12:13], 0
	s_branch .LBB0_130

; DI unsigned xb_ld(unsigned* p) { return __hip_atomic_load(p, __ATOMIC_RELAXED, __HIP_MEMORY_SCOPE_AGENT); }
; DI unsigned xb_add(unsigned* p, unsigned v) { return __hip_atomic_fetch_add(p, v, __ATOMIC_RELAXED, __HIP_MEMORY_SCOPE_AGENT); }
; #define XB_SPIN(cond, bar) do { unsigned _sp = 0; while (cond) { __builtin_amdgcn_s_sleep(1); \
;     if ((++_sp & 255u) == 0u) { if (xb_ld(&(bar)[XB_TMO])) break; if (_sp > XB_SPIN_CAP) { atomicAdd(&(bar)[XB_TMO], 1u); break; } } } } while (0)
; template <bool FIRST>
; DI void xcd_barrier(XcdBarrier& b) {
;   asm volatile("s_waitcnt vmcnt(0)" ::: "memory");
;   __syncthreads();
;   if (threadIdx.x == 0) {
;     unsigned* bar = b.bar;
;     asm volatile("" : "+s"(bar));
;     __builtin_amdgcn_s_waitcnt(0);
;     const unsigned bx = b.st[2];
;     if (FIRST) { unsigned n0, n1; xcd_barrier_complete(bar, bx, n0, n1); b.st[0] = n0; b.st[1] = n1; }
;     const unsigned nloc = b.st[0], nx = b.st[1];
;     const unsigned old = xb_add(&bar[XB_XSUB(bx)], 1u);
;     const unsigned gen = old / nloc;
;     if (old + 1u == (gen + 1u) * nloc) {
;       __builtin_amdgcn_fence(__ATOMIC_RELEASE, "agent");
;       asm volatile("s_waitcnt vmcnt(0)" ::: "memory");
;       const unsigned og = xb_add(&bar[XB_TOP], 1u);
;       const unsigned tg = og / nx;
;       if (og + 1u == (tg + 1u) * nx) xb_add(&bar[XB_TOPGEN], 1u);
;       else XB_SPIN(xb_ld(&bar[XB_TOPGEN]) == tg, bar);
;       __builtin_amdgcn_fence(__ATOMIC_ACQUIRE, "agent");
;       xb_add(&bar[XB_XGEN(bx)], 1u);
;       asm volatile("s_waitcnt vmcnt(0)" ::: "memory");
;     } else {
;       XB_SPIN(xb_ld(&bar[XB_XGEN(bx)]) == gen, bar);
.LBB0_390:
	s_mul_i32 s0, s48, 6
	s_add_i32 s28, s0, 3
	s_cmp_ge_i32 s28, s59
	s_cbranch_scc1 .LBB0_422
	s_waitcnt vmcnt(0)
	s_waitcnt lgkmcnt(0)
	s_barrier
	s_and_saveexec_b64 s[0:1], s[60:61]
	s_cbranch_execz .LBB0_421
	v_readlane_b32 s4, v253, 1
	v_readlane_b32 s5, v253, 2
	s_waitcnt vmcnt(0) expcnt(0) lgkmcnt(0)
	ds_read_b32 v0, v163
	ds_read_b32 v4, v172
	ds_read_b32 v1, v173
	s_waitcnt lgkmcnt(2)
	v_readfirstlane_b32 s2, v0
	s_lshl_b32 s29, s2, 6
	s_add_i32 s2, s29, 0x500
	s_lshl_b64 s[6:7], s[2:3], 2
	s_add_u32 s6, s4, s6
	s_addc_u32 s7, s5, s7
	v_mov_b64_e32 v[2:3], s[6:7]
	flat_atomic_add v2, v[2:3], v174 sc0
	s_waitcnt lgkmcnt(0)
	v_cvt_f32_u32_e32 v0, v4
	v_sub_u32_e32 v3, 0, v4
	v_rcp_iflag_f32_e32 v0, v0
	s_nop 0
	v_mul_f32_e32 v0, 0x4f7ffffe, v0
	v_cvt_u32_f32_e32 v0, v0
	v_mul_lo_u32 v3, v3, v0
	v_mul_hi_u32 v3, v0, v3
	v_add_u32_e32 v0, v0, v3
	s_waitcnt vmcnt(0)
	v_mul_hi_u32 v0, v2, v0
	v_mul_lo_u32 v3, v0, v4
	v_sub_u32_e32 v3, v2, v3
	v_add_u32_e32 v5, 1, v0
	v_cmp_ge_u32_e32 vcc, v3, v4
	v_add_u32_e32 v2, 1, v2
	s_nop 0
	v_cndmask_b32_e32 v0, v0, v5, vcc
	v_sub_u32_e32 v5, v3, v4
	v_cndmask_b32_e32 v3, v3, v5, vcc
	v_add_u32_e32 v5, 1, v0
	v_cmp_ge_u32_e32 vcc, v3, v4
	s_nop 1
	v_cndmask_b32_e32 v0, v0, v5, vcc
	v_mul_lo_u32 v3, v4, v0
	v_add_u32_e32 v3, v3, v4
	v_cmp_ne_u32_e32 vcc, v2, v3
	s_and_saveexec_b64 s[6:7], vcc
	s_xor_b64 s[6:7], exec, s[6:7]
	s_cbranch_execz .LBB0_405
	s_add_i32 s2, s29, 0x900
	s_add_u32 s10, s4, 0x3500
	s_addc_u32 s11, s5, 0
	v_mov_b64_e32 v[2:3], s[10:11]
	global_load_dword v1, v[2:3], off sc1
	s_waitcnt vmcnt(0) lgkmcnt(0)
	v_cmp_eq_u32_e32 vcc, v1, v0
	s_and_saveexec_b64 s[8:9], vcc
	s_cbranch_execz .LBB0_404
	s_mov_b32 s2, 1
	s_mov_b64 s[12:13], 0
	s_branch .LBB0_396

; DI unsigned xb_ld(unsigned* p) { return __hip_atomic_load(p, __ATOMIC_RELAXED, __HIP_MEMORY_SCOPE_AGENT); }
; DI unsigned xb_add(unsigned* p, unsigned v) { return __hip_atomic_fetch_add(p, v, __ATOMIC_RELAXED, __HIP_MEMORY_SCOPE_AGENT); }
; #define XB_SPIN(cond, bar) do { unsigned _sp = 0; while (cond) { __builtin_amdgcn_s_sleep(1); \
;     if ((++_sp & 255u) == 0u) { if (xb_ld(&(bar)[XB_TMO])) break; if (_sp > XB_SPIN_CAP) { atomicAdd(&(bar)[XB_TMO], 1u); break; } } } } while (0)
; template <bool FIRST>
; DI void xcd_barrier(XcdBarrier& b) {
;   asm volatile("s_waitcnt vmcnt(0)" ::: "memory");
;   __syncthreads();
;   if (threadIdx.x == 0) {
;     unsigned* bar = b.bar;
;     asm volatile("" : "+s"(bar));
;     __builtin_amdgcn_s_waitcnt(0);
;     const unsigned bx = b.st[2];
;     if (FIRST) { unsigned n0, n1; xcd_barrier_complete(bar, bx, n0, n1); b.st[0] = n0; b.st[1] = n1; }
;     const unsigned nloc = b.st[0], nx = b.st[1];
;     const unsigned old = xb_add(&bar[XB_XSUB(bx)], 1u);
;     const unsigned gen = old / nloc;
;     if (old + 1u == (gen + 1u) * nloc) {
;       __builtin_amdgcn_fence(__ATOMIC_RELEASE, "agent");
;       asm volatile("s_waitcnt vmcnt(0)" ::: "memory");
;       const unsigned og = xb_add(&bar[XB_TOP], 1u);
;       const unsigned tg = og / nx;
;       if (og + 1u == (tg + 1u) * nx) xb_add(&bar[XB_TOPGEN], 1u);
;       else XB_SPIN(xb_ld(&bar[XB_TOPGEN]) == tg, bar);
;       __builtin_amdgcn_fence(__ATOMIC_ACQUIRE, "agent");
;       xb_add(&bar[XB_XGEN(bx)], 1u);
;       asm volatile("s_waitcnt vmcnt(0)" ::: "memory");
;     } else {
;       XB_SPIN(xb_ld(&bar[XB_XGEN(bx)]) == gen, bar);
.LBB0_769:
	v_readlane_b32 s48, v254, 17
	s_mul_i32 s0, s48, 6
	s_add_i32 s28, s0, 4
	s_cmp_ge_i32 s28, s59
	v_readlane_b32 s49, v254, 18
	s_cbranch_scc1 .LBB0_801
	s_waitcnt vmcnt(0)
	s_waitcnt lgkmcnt(0)
	s_barrier
	s_and_saveexec_b64 s[0:1], s[60:61]
	s_cbranch_execz .LBB0_800
	v_readlane_b32 s4, v253, 1
	v_readlane_b32 s5, v253, 2
	s_waitcnt vmcnt(0) expcnt(0) lgkmcnt(0)
	ds_read_b32 v0, v163
	ds_read_b32 v4, v172
	ds_read_b32 v1, v173
	s_waitcnt lgkmcnt(2)
	v_readfirstlane_b32 s2, v0
	s_lshl_b32 s29, s2, 6
	s_add_i32 s2, s29, 0x500
	s_lshl_b64 s[6:7], s[2:3], 2
	s_add_u32 s6, s4, s6
	s_addc_u32 s7, s5, s7
	v_mov_b64_e32 v[2:3], s[6:7]
	flat_atomic_add v2, v[2:3], v174 sc0
	s_waitcnt lgkmcnt(0)
	v_cvt_f32_u32_e32 v0, v4
	v_sub_u32_e32 v3, 0, v4
	v_rcp_iflag_f32_e32 v0, v0
	s_nop 0
	v_mul_f32_e32 v0, 0x4f7ffffe, v0
	v_cvt_u32_f32_e32 v0, v0
	v_mul_lo_u32 v3, v3, v0
	v_mul_hi_u32 v3, v0, v3
	v_add_u32_e32 v0, v0, v3
	s_waitcnt vmcnt(0)
	v_mul_hi_u32 v0, v2, v0
	v_mul_lo_u32 v3, v0, v4
	v_sub_u32_e32 v3, v2, v3
	v_add_u32_e32 v5, 1, v0
	v_cmp_ge_u32_e32 vcc, v3, v4
	v_add_u32_e32 v2, 1, v2
	s_nop 0
	v_cndmask_b32_e32 v0, v0, v5, vcc
	v_sub_u32_e32 v5, v3, v4
	v_cndmask_b32_e32 v3, v3, v5, vcc
	v_add_u32_e32 v5, 1, v0
	v_cmp_ge_u32_e32 vcc, v3, v4
	s_nop 1
	v_cndmask_b32_e32 v0, v0, v5, vcc
	v_mul_lo_u32 v3, v4, v0
	v_add_u32_e32 v3, v3, v4
	v_cmp_ne_u32_e32 vcc, v2, v3
	s_and_saveexec_b64 s[6:7], vcc
	s_xor_b64 s[6:7], exec, s[6:7]
	s_cbranch_execz .LBB0_784
	s_add_i32 s2, s29, 0x900
	s_add_u32 s10, s4, 0x3500
	s_addc_u32 s11, s5, 0
	v_mov_b64_e32 v[2:3], s[10:11]
	global_load_dword v1, v[2:3], off sc1
	s_waitcnt vmcnt(0) lgkmcnt(0)
	v_cmp_eq_u32_e32 vcc, v1, v0
	s_and_saveexec_b64 s[8:9], vcc
	s_cbranch_execz .LBB0_783
	s_mov_b32 s2, 1
	s_mov_b64 s[12:13], 0
	s_branch .LBB0_775

; DI unsigned xb_ld(unsigned* p) { return __hip_atomic_load(p, __ATOMIC_RELAXED, __HIP_MEMORY_SCOPE_AGENT); }
; DI unsigned xb_add(unsigned* p, unsigned v) { return __hip_atomic_fetch_add(p, v, __ATOMIC_RELAXED, __HIP_MEMORY_SCOPE_AGENT); }
; #define XB_SPIN(cond, bar) do { unsigned _sp = 0; while (cond) { __builtin_amdgcn_s_sleep(1); \
;     if ((++_sp & 255u) == 0u) { if (xb_ld(&(bar)[XB_TMO])) break; if (_sp > XB_SPIN_CAP) { atomicAdd(&(bar)[XB_TMO], 1u); break; } } } } while (0)
; template <bool FIRST>
; DI void xcd_barrier(XcdBarrier& b) {
;   asm volatile("s_waitcnt vmcnt(0)" ::: "memory");
;   __syncthreads();
;   if (threadIdx.x == 0) {
;     unsigned* bar = b.bar;
;     asm volatile("" : "+s"(bar));
;     __builtin_amdgcn_s_waitcnt(0);
;     const unsigned bx = b.st[2];
;     if (FIRST) { unsigned n0, n1; xcd_barrier_complete(bar, bx, n0, n1); b.st[0] = n0; b.st[1] = n1; }
;     const unsigned nloc = b.st[0], nx = b.st[1];
;     const unsigned old = xb_add(&bar[XB_XSUB(bx)], 1u);
;     const unsigned gen = old / nloc;
;     if (old + 1u == (gen + 1u) * nloc) {
;       __builtin_amdgcn_fence(__ATOMIC_RELEASE, "agent");
;       asm volatile("s_waitcnt vmcnt(0)" ::: "memory");
;       const unsigned og = xb_add(&bar[XB_TOP], 1u);
;       const unsigned tg = og / nx;
;       if (og + 1u == (tg + 1u) * nx) xb_add(&bar[XB_TOPGEN], 1u);
;       else XB_SPIN(xb_ld(&bar[XB_TOPGEN]) == tg, bar);
;       __builtin_amdgcn_fence(__ATOMIC_ACQUIRE, "agent");
;       xb_add(&bar[XB_XGEN(bx)], 1u);
;       asm volatile("s_waitcnt vmcnt(0)" ::: "memory");
;     } else {
;       XB_SPIN(xb_ld(&bar[XB_XGEN(bx)]) == gen, bar);
.LBB0_1018:
	v_readlane_b32 s48, v254, 17
	s_mul_i32 s0, s48, 6
	s_add_i32 s0, s0, 5
	v_readlane_b32 s72, v254, 15
	s_cmp_ge_i32 s0, s59
	v_readlane_b32 s73, v254, 16
	v_readlane_b32 s49, v254, 18
	s_cbranch_scc1 .LBB0_1050
	s_waitcnt vmcnt(0)
	s_waitcnt lgkmcnt(0)
	s_barrier
	s_and_saveexec_b64 s[0:1], s[60:61]
	s_cbranch_execz .LBB0_1049
	v_readlane_b32 s4, v253, 1
	v_readlane_b32 s5, v253, 2
	s_waitcnt vmcnt(0) expcnt(0) lgkmcnt(0)
	ds_read_b32 v0, v163
	ds_read_b32 v4, v172
	ds_read_b32 v1, v173
	s_waitcnt lgkmcnt(2)
	v_readfirstlane_b32 s2, v0
	s_lshl_b32 s28, s2, 6
	s_add_i32 s2, s28, 0x500
	s_lshl_b64 s[6:7], s[2:3], 2
	s_add_u32 s6, s4, s6
	s_addc_u32 s7, s5, s7
	v_mov_b64_e32 v[2:3], s[6:7]
	flat_atomic_add v2, v[2:3], v174 sc0
	s_waitcnt lgkmcnt(0)
	v_cvt_f32_u32_e32 v0, v4
	v_sub_u32_e32 v3, 0, v4
	v_rcp_iflag_f32_e32 v0, v0
	s_nop 0
	v_mul_f32_e32 v0, 0x4f7ffffe, v0
	v_cvt_u32_f32_e32 v0, v0
	v_mul_lo_u32 v3, v3, v0
	v_mul_hi_u32 v3, v0, v3
	v_add_u32_e32 v0, v0, v3
	s_waitcnt vmcnt(0)
	v_mul_hi_u32 v0, v2, v0
	v_mul_lo_u32 v3, v0, v4
	v_sub_u32_e32 v3, v2, v3
	v_add_u32_e32 v5, 1, v0
	v_cmp_ge_u32_e32 vcc, v3, v4
	v_add_u32_e32 v2, 1, v2
	s_nop 0
	v_cndmask_b32_e32 v0, v0, v5, vcc
	v_sub_u32_e32 v5, v3, v4
	v_cndmask_b32_e32 v3, v3, v5, vcc
	v_add_u32_e32 v5, 1, v0
	v_cmp_ge_u32_e32 vcc, v3, v4
	s_nop 1
	v_cndmask_b32_e32 v0, v0, v5, vcc
	v_mul_lo_u32 v3, v4, v0
	v_add_u32_e32 v3, v3, v4
	v_cmp_ne_u32_e32 vcc, v2, v3
	s_and_saveexec_b64 s[6:7], vcc
	s_xor_b64 s[6:7], exec, s[6:7]
	s_cbranch_execz .LBB0_1033
	s_add_i32 s2, s28, 0x900
	s_add_u32 s10, s4, 0x3500
	s_addc_u32 s11, s5, 0
	v_mov_b64_e32 v[2:3], s[10:11]
	global_load_dword v1, v[2:3], off sc1
	s_waitcnt vmcnt(0) lgkmcnt(0)
	v_cmp_eq_u32_e32 vcc, v1, v0
	s_and_saveexec_b64 s[8:9], vcc
	s_cbranch_execz .LBB0_1032
	s_mov_b32 s2, 1
	s_mov_b64 s[12:13], 0
	s_branch .LBB0_1024

; DI unsigned xb_ld(unsigned* p) { return __hip_atomic_load(p, __ATOMIC_RELAXED, __HIP_MEMORY_SCOPE_AGENT); }
; DI unsigned xb_add(unsigned* p, unsigned v) { return __hip_atomic_fetch_add(p, v, __ATOMIC_RELAXED, __HIP_MEMORY_SCOPE_AGENT); }
; #define XB_SPIN(cond, bar) do { unsigned _sp = 0; while (cond) { __builtin_amdgcn_s_sleep(1); \
;     if ((++_sp & 255u) == 0u) { if (xb_ld(&(bar)[XB_TMO])) break; if (_sp > XB_SPIN_CAP) { atomicAdd(&(bar)[XB_TMO], 1u); break; } } } } while (0)
; template <bool FIRST>
; DI void xcd_barrier(XcdBarrier& b) {
;   asm volatile("s_waitcnt vmcnt(0)" ::: "memory");
;   __syncthreads();
;   if (threadIdx.x == 0) {
;     unsigned* bar = b.bar;
;     asm volatile("" : "+s"(bar));
;     __builtin_amdgcn_s_waitcnt(0);
;     const unsigned bx = b.st[2];
;     if (FIRST) { unsigned n0, n1; xcd_barrier_complete(bar, bx, n0, n1); b.st[0] = n0; b.st[1] = n1; }
;     const unsigned nloc = b.st[0], nx = b.st[1];
;     const unsigned old = xb_add(&bar[XB_XSUB(bx)], 1u);
;     const unsigned gen = old / nloc;
;     if (old + 1u == (gen + 1u) * nloc) {
;       __builtin_amdgcn_fence(__ATOMIC_RELEASE, "agent");
;       asm volatile("s_waitcnt vmcnt(0)" ::: "memory");
;       const unsigned og = xb_add(&bar[XB_TOP], 1u);
;       const unsigned tg = og / nx;
;       if (og + 1u == (tg + 1u) * nx) xb_add(&bar[XB_TOPGEN], 1u);
;       else XB_SPIN(xb_ld(&bar[XB_TOPGEN]) == tg, bar);
;       __builtin_amdgcn_fence(__ATOMIC_ACQUIRE, "agent");
;       xb_add(&bar[XB_XGEN(bx)], 1u);
;       asm volatile("s_waitcnt vmcnt(0)" ::: "memory");
;     } else {
;       XB_SPIN(xb_ld(&bar[XB_XGEN(bx)]) == gen, bar);
.LBB0_1100:
	v_readlane_b32 s0, v254, 14
	s_add_i32 s0, s0, 7
	s_cmp_ge_i32 s0, s59
	s_cbranch_scc1 .Ltr_109
	s_waitcnt vmcnt(0)
	s_waitcnt lgkmcnt(0)
	s_barrier
	s_and_saveexec_b64 s[0:1], s[60:61]
	s_cbranch_execz .Ltr_108
	v_readlane_b32 s4, v253, 1
	v_readlane_b32 s5, v253, 2
	s_waitcnt vmcnt(0) expcnt(0) lgkmcnt(0)
	ds_read_b32 v0, v163
	ds_read_b32 v4, v172
	ds_read_b32 v1, v173
	s_waitcnt lgkmcnt(2)
	v_readfirstlane_b32 s2, v0
	s_lshl_b32 s28, s2, 6
	s_add_i32 s2, s28, 0x500
	s_lshl_b64 s[6:7], s[2:3], 2
	s_add_u32 s6, s4, s6
	s_addc_u32 s7, s5, s7
	v_mov_b64_e32 v[2:3], s[6:7]
	flat_atomic_add v2, v[2:3], v174 sc0
	s_waitcnt lgkmcnt(0)
	v_cvt_f32_u32_e32 v0, v4
	v_sub_u32_e32 v3, 0, v4
	v_rcp_iflag_f32_e32 v0, v0
	s_nop 0
	v_mul_f32_e32 v0, 0x4f7ffffe, v0
	v_cvt_u32_f32_e32 v0, v0
	v_mul_lo_u32 v3, v3, v0
	v_mul_hi_u32 v3, v0, v3
	v_add_u32_e32 v0, v0, v3
	s_waitcnt vmcnt(0)
	v_mul_hi_u32 v0, v2, v0
	v_mul_lo_u32 v3, v0, v4
	v_sub_u32_e32 v3, v2, v3
	v_add_u32_e32 v5, 1, v0
	v_cmp_ge_u32_e32 vcc, v3, v4
	v_add_u32_e32 v2, 1, v2
	s_nop 0
	v_cndmask_b32_e32 v0, v0, v5, vcc
	v_sub_u32_e32 v5, v3, v4
	v_cndmask_b32_e32 v3, v3, v5, vcc
	v_add_u32_e32 v5, 1, v0
	v_cmp_ge_u32_e32 vcc, v3, v4
	s_nop 1
	v_cndmask_b32_e32 v0, v0, v5, vcc
	v_mul_lo_u32 v3, v4, v0
	v_add_u32_e32 v3, v3, v4
	v_cmp_ne_u32_e32 vcc, v2, v3
	s_and_saveexec_b64 s[6:7], vcc
	s_xor_b64 s[6:7], exec, s[6:7]
	s_cbranch_execz .LBB0_1115
	s_add_i32 s2, s28, 0x900
	s_add_u32 s10, s4, 0x3500
	s_addc_u32 s11, s5, 0
	v_mov_b64_e32 v[2:3], s[10:11]
	global_load_dword v1, v[2:3], off sc1
	s_waitcnt vmcnt(0) lgkmcnt(0)
	v_cmp_eq_u32_e32 vcc, v1, v0
	s_and_saveexec_b64 s[8:9], vcc
	s_cbranch_execz .LBB0_1114
	s_mov_b32 s2, 1
	s_mov_b64 s[12:13], 0
	s_branch .LBB0_1106
